# weight-conversion loops: f32 weight loads marked nt (read once)
# speedup vs baseline: 1.0040x; 1.0040x over previous
; DI unsigned pack2(float lo, float hi) { const f32x2 v = (f32x2){lo, hi}; return __builtin_bit_cast(unsigned, __builtin_convertvector(v, bf16x2_t)); }
; DI void conv_jobs(const ConvJob j0, const ConvJob j1, const ConvJob j2, const ConvJob j3, char* shm) {
;     ...
;     for (int L = bx; L < c4; L += gridDim.x) {
;         const float* __restrict__ src = j0.src; bf16_t* __restrict__ dst = j0.dst; int ldsrc = j0.ldsrc, K = j0.K, mode = j0.mode, base = 0;
;         if (L >= c1) { src = j1.src; dst = j1.dst; ldsrc = j1.ldsrc; K = j1.K; mode = j1.mode; base = c1; }
;         if (L >= c2) { src = j2.src; dst = j2.dst; ldsrc = j2.ldsrc; K = j2.K; mode = j2.mode; base = c2; }
;         if (L >= c3) { src = j3.src; dst = j3.dst; ldsrc = j3.ldsrc; K = j3.K; mode = j3.mode; base = c3; }
;         const int nk = K / 64, Ll = L - base, tk = Ll % nk, ts = Ll / nk, n0 = ts * 256;
;         __syncthreads();
;         f32x4 v[8];
; #pragma unroll
;         for (int i = 0; i < 8; ++i) { const int e = tid + i * NTHR, kk = e >> 6, n4 = (e & 63) * 4;
;             const int scol = mode == 1 ? ((n4 >> 7) ? 2816 + ts * 128 + (n4 & 127) : ts * 128 + n4) : n0 + n4;
;             v[i] = *(const f32x4*)(src + (size_t)(tk * 64 + kk) * ldsrc + scol); }
; #pragma unroll
;         for (int i = 0; i < 8; ++i) { const int e = tid + i * NTHR, kk = e >> 6, n4 = (e & 63) * 4; *(f32x4*)(tile + kk * 260 + (n4 ^ (((kk >> 3) & 7) << 3))) = v[i]; }
;         __syncthreads();
; #pragma unroll
;         for (int i = 0; i < 4; ++i) { const int n = (tid >> 3) + 64 * i, m = tid & 7, kc = m * 8; const float* tp = tile + kc * 260 + (n ^ (m << 3)); u32x4 w;
;             w.x = pack2(tp[0], tp[260]); w.y = pack2(tp[2 * 260], tp[3 * 260]); w.z = pack2(tp[4 * 260], tp[5 * 260]); w.w = pack2(tp[6 * 260], tp[7 * 260]);
;             *(u32x4*)(dst + (size_t)(n0 + n) * K + tk * 64 + kc) = w; }
.LBB0_89:
	v_cvt_f32_ubyte0_e32 v29, s8
	v_rcp_iflag_f32_e32 v29, v29
	s_sub_i32 s5, 0, s8
	s_add_i32 s1, s12, s1
	s_abs_i32 s13, s1
	v_mul_f32_e32 v29, 0x4f7ffffe, v29
	v_cvt_u32_f32_e32 v29, v29
	s_ashr_i32 s9, s1, 31
	s_barrier
	v_readfirstlane_b32 s14, v29
	s_mul_i32 s5, s5, s14
	s_mul_hi_u32 s5, s14, s5
	s_add_i32 s14, s14, s5
	s_mul_hi_u32 s5, s13, s14
	s_mul_i32 s14, s5, s8
	s_sub_i32 s13, s13, s14
	s_add_i32 s15, s5, 1
	s_sub_i32 s14, s13, s8
	s_cmp_ge_u32 s13, s8
	s_cselect_b32 s5, s15, s5
	s_cselect_b32 s13, s14, s13
	s_add_i32 s14, s5, 1
	s_cmp_ge_u32 s13, s8
	s_cselect_b32 s5, s14, s5
	s_xor_b32 s5, s5, s9
	s_sub_i32 s5, s5, s9
	s_mul_i32 s8, s5, s8
	s_sub_i32 s8, s1, s8
	s_lshl_b32 s1, s5, 8
	s_lshl_b32 s8, s8, 6
	v_or_b32_e32 v29, s1, v1
	v_lshl_add_u32 v30, s5, 7, v7
	v_cndmask_b32_e64 v30, v29, v30, s[10:11]
	v_add_u32_e32 v29, s8, v6
	v_mad_i64_i32 v[32:33], s[10:11], s4, v29, 0
	v_ashrrev_i32_e32 v31, 31, v30
	v_lshl_add_u64 v[32:33], v[32:33], 2, s[6:7]
	v_lshlrev_b64 v[54:55], 2, v[30:31]
	v_add_u32_e32 v29, s8, v8
	v_lshl_add_u64 v[30:31], v[32:33], 0, v[54:55]
	v_mad_i64_i32 v[32:33], s[10:11], s4, v29, 0
	v_add_u32_e32 v29, s8, v9
	v_mad_i64_i32 v[38:39], s[10:11], s4, v29, 0
	v_add_u32_e32 v29, s8, v10
	v_mad_i64_i32 v[40:41], s[10:11], s4, v29, 0
	v_add_u32_e32 v29, s8, v11
	v_mad_i64_i32 v[46:47], s[10:11], s4, v29, 0
	v_add_u32_e32 v29, s8, v12
	v_mad_i64_i32 v[48:49], s[10:11], s4, v29, 0
	v_add_u32_e32 v29, s8, v13
	v_mad_i64_i32 v[56:57], s[10:11], s4, v29, 0
	v_add_u32_e32 v29, s8, v14
	v_mad_i64_i32 v[58:59], s[4:5], s4, v29, 0
	v_lshl_add_u64 v[32:33], v[32:33], 2, s[6:7]
	v_lshl_add_u64 v[38:39], v[38:39], 2, s[6:7]
	v_lshl_add_u64 v[40:41], v[40:41], 2, s[6:7]
	v_lshl_add_u64 v[46:47], v[46:47], 2, s[6:7]
	v_lshl_add_u64 v[48:49], v[48:49], 2, s[6:7]
	v_lshl_add_u64 v[56:57], v[56:57], 2, s[6:7]
	v_lshl_add_u64 v[58:59], v[58:59], 2, s[6:7]
	v_lshl_add_u64 v[34:35], v[32:33], 0, v[54:55]
	v_lshl_add_u64 v[38:39], v[38:39], 0, v[54:55]
	v_lshl_add_u64 v[42:43], v[40:41], 0, v[54:55]
	v_lshl_add_u64 v[46:47], v[46:47], 0, v[54:55]
	v_lshl_add_u64 v[50:51], v[48:49], 0, v[54:55]
	v_lshl_add_u64 v[56:57], v[56:57], 0, v[54:55]
	v_lshl_add_u64 v[58:59], v[58:59], 0, v[54:55]
	global_load_dwordx4 v[30:33], v[30:31], off nt
	s_nop 0
	global_load_dwordx4 v[34:37], v[34:35], off nt
	s_nop 0
	global_load_dwordx4 v[38:41], v[38:39], off nt
	s_nop 0
	global_load_dwordx4 v[42:45], v[42:43], off nt
	s_nop 0
	global_load_dwordx4 v[46:49], v[46:47], off nt
	s_nop 0
	global_load_dwordx4 v[50:53], v[50:51], off nt
	s_nop 0
	global_load_dwordx4 v[54:57], v[56:57], off nt
	s_nop 0
	global_load_dwordx4 v[58:61], v[58:59], off nt
	v_add_u32_e32 v29, s1, v4
	v_mad_i64_i32 v[62:63], s[4:5], s0, v29, 0
	s_ashr_i32 s9, s8, 31
	s_lshl_b64 s[4:5], s[8:9], 1
	s_add_u32 s2, s2, s4
	s_addc_u32 s3, s3, s5
	v_lshl_add_u64 v[64:65], s[2:3], 0, v[2:3]
	s_add_i32 s12, s12, s70
	s_cmpk_gt_i32 s12, 0x24f
	s_waitcnt vmcnt(7)
	ds_write_b128 v15, v[30:33]
	s_waitcnt vmcnt(6)
	ds_write_b128 v16, v[34:37]
	s_waitcnt vmcnt(5)
	ds_write_b128 v17, v[38:41]
	s_waitcnt vmcnt(4)
	ds_write_b128 v18, v[42:45]
	s_waitcnt vmcnt(3)
	ds_write_b128 v19, v[46:49]
	s_waitcnt vmcnt(2)
	ds_write_b128 v20, v[50:53]
	s_waitcnt vmcnt(1)
	ds_write_b128 v21, v[54:57]
	s_waitcnt vmcnt(0)
	ds_write_b128 v22, v[58:61]
	s_waitcnt lgkmcnt(0)
	s_barrier
	ds_read_b32 v29, v5
	ds_read_b32 v30, v5 offset:1040
	ds_read_b32 v31, v5 offset:2080
	ds_read_b32 v32, v5 offset:3120
	ds_read_b32 v33, v5 offset:4160
	ds_read_b32 v36, v5 offset:5200
	ds_read_b32 v37, v5 offset:6240
	ds_read_b32 v38, v5 offset:7280
	s_waitcnt lgkmcnt(6)
	v_cvt_pk_bf16_f32 v30, v29, v30
	s_waitcnt lgkmcnt(4)
	v_cvt_pk_bf16_f32 v31, v31, v32
	s_waitcnt lgkmcnt(2)
	v_cvt_pk_bf16_f32 v32, v33, v36
	v_lshl_add_u64 v[34:35], v[62:63], 1, v[64:65]
	s_waitcnt lgkmcnt(0)
	v_cvt_pk_bf16_f32 v33, v37, v38
	ds_read_b32 v29, v24
	ds_read_b32 v36, v24 offset:1040
	ds_read_b32 v37, v24 offset:2080
	ds_read_b32 v38, v24 offset:3120
	ds_read_b32 v39, v24 offset:4160
	ds_read_b32 v40, v24 offset:5200
	ds_read_b32 v41, v24 offset:6240
	ds_read_b32 v42, v24 offset:7280
	global_store_dwordx4 v[34:35], v[30:33], off
	s_waitcnt lgkmcnt(6)
	s_nop 0
	v_cvt_pk_bf16_f32 v30, v29, v36
	v_add_u32_e32 v29, s1, v23
	s_waitcnt lgkmcnt(4)
	v_cvt_pk_bf16_f32 v31, v37, v38
	s_waitcnt lgkmcnt(2)
	v_cvt_pk_bf16_f32 v32, v39, v40
	s_waitcnt lgkmcnt(0)
	v_cvt_pk_bf16_f32 v33, v41, v42
	v_mad_i64_i32 v[34:35], s[2:3], s0, v29, 0
	ds_read_b32 v29, v26
	ds_read_b32 v36, v26 offset:1040
	ds_read_b32 v37, v26 offset:2080
	ds_read_b32 v38, v26 offset:3120
	ds_read_b32 v39, v26 offset:4160
	ds_read_b32 v40, v26 offset:5200
	ds_read_b32 v41, v26 offset:6240
	ds_read_b32 v42, v26 offset:7280
	v_lshl_add_u64 v[34:35], v[34:35], 1, v[64:65]
	global_store_dwordx4 v[34:35], v[30:33], off
	s_waitcnt lgkmcnt(6)
	s_nop 0
	v_cvt_pk_bf16_f32 v30, v29, v36
	v_add_u32_e32 v29, s1, v25
	s_waitcnt lgkmcnt(4)
	v_cvt_pk_bf16_f32 v31, v37, v38
	s_waitcnt lgkmcnt(2)
	v_cvt_pk_bf16_f32 v32, v39, v40
	s_waitcnt lgkmcnt(0)
	v_cvt_pk_bf16_f32 v33, v41, v42
	v_mad_i64_i32 v[34:35], s[2:3], s0, v29, 0
	ds_read_b32 v29, v28
	ds_read_b32 v36, v28 offset:1040
	ds_read_b32 v37, v28 offset:2080
	ds_read_b32 v38, v28 offset:3120
	ds_read_b32 v39, v28 offset:4160
	ds_read_b32 v40, v28 offset:5200
	ds_read_b32 v41, v28 offset:6240
	ds_read_b32 v42, v28 offset:7280
	v_lshl_add_u64 v[34:35], v[34:35], 1, v[64:65]
	global_store_dwordx4 v[34:35], v[30:33], off
	s_waitcnt lgkmcnt(6)
	s_nop 0
	v_cvt_pk_bf16_f32 v30, v29, v36
	v_add_u32_e32 v29, s1, v27
	v_mad_i64_i32 v[34:35], s[0:1], s0, v29, 0
	s_waitcnt lgkmcnt(4)
	v_cvt_pk_bf16_f32 v31, v37, v38
	s_waitcnt lgkmcnt(2)
	v_cvt_pk_bf16_f32 v32, v39, v40
	s_waitcnt lgkmcnt(0)
	v_cvt_pk_bf16_f32 v33, v41, v42
	v_lshl_add_u64 v[34:35], v[34:35], 1, v[64:65]
	global_store_dwordx4 v[34:35], v[30:33], off
	s_cbranch_scc1 .LBB0_96

; DI unsigned pack2(float lo, float hi) { const f32x2 v = (f32x2){lo, hi}; return __builtin_bit_cast(unsigned, __builtin_convertvector(v, bf16x2_t)); }
; DI void conv_jobs(const ConvJob j0, const ConvJob j1, const ConvJob j2, const ConvJob j3, char* shm) {
;     ...
;     for (int L = bx; L < c4; L += gridDim.x) {
;         const float* __restrict__ src = j0.src; bf16_t* __restrict__ dst = j0.dst; int ldsrc = j0.ldsrc, K = j0.K, mode = j0.mode, base = 0;
;         if (L >= c1) { src = j1.src; dst = j1.dst; ldsrc = j1.ldsrc; K = j1.K; mode = j1.mode; base = c1; }
;         if (L >= c2) { src = j2.src; dst = j2.dst; ldsrc = j2.ldsrc; K = j2.K; mode = j2.mode; base = c2; }
;         if (L >= c3) { src = j3.src; dst = j3.dst; ldsrc = j3.ldsrc; K = j3.K; mode = j3.mode; base = c3; }
;         const int nk = K / 64, Ll = L - base, tk = Ll % nk, ts = Ll / nk, n0 = ts * 256;
;         __syncthreads();
;         f32x4 v[8];
; #pragma unroll
;         for (int i = 0; i < 8; ++i) { const int e = tid + i * NTHR, kk = e >> 6, n4 = (e & 63) * 4;
;             const int scol = mode == 1 ? ((n4 >> 7) ? 2816 + ts * 128 + (n4 & 127) : ts * 128 + n4) : n0 + n4;
;             v[i] = *(const f32x4*)(src + (size_t)(tk * 64 + kk) * ldsrc + scol); }
; #pragma unroll
;         for (int i = 0; i < 8; ++i) { const int e = tid + i * NTHR, kk = e >> 6, n4 = (e & 63) * 4; *(f32x4*)(tile + kk * 260 + (n4 ^ (((kk >> 3) & 7) << 3))) = v[i]; }
;         __syncthreads();
; #pragma unroll
;         for (int i = 0; i < 4; ++i) { const int n = (tid >> 3) + 64 * i, m = tid & 7, kc = m * 8; const float* tp = tile + kc * 260 + (n ^ (m << 3)); u32x4 w;
;             w.x = pack2(tp[0], tp[260]); w.y = pack2(tp[2 * 260], tp[3 * 260]); w.z = pack2(tp[4 * 260], tp[5 * 260]); w.w = pack2(tp[6 * 260], tp[7 * 260]);
;             *(u32x4*)(dst + (size_t)(n0 + n) * K + tk * 64 + kc) = w; }
.LBB0_948:
	v_cvt_f32_ubyte0_e32 v28, s12
	v_rcp_iflag_f32_e32 v28, v28
	s_sub_i32 s9, 0, s12
	s_add_i32 s5, s26, s5
	s_abs_i32 s30, s5
	v_mul_f32_e32 v28, 0x4f7ffffe, v28
	v_cvt_u32_f32_e32 v28, v28
	s_ashr_i32 s13, s5, 31
	s_barrier
	v_readfirstlane_b32 s31, v28
	s_mul_i32 s9, s9, s31
	s_mul_hi_u32 s9, s31, s9
	s_add_i32 s31, s31, s9
	s_mul_hi_u32 s9, s30, s31
	s_mul_i32 s31, s9, s12
	s_sub_i32 s30, s30, s31
	s_add_i32 s34, s9, 1
	s_sub_i32 s31, s30, s12
	s_cmp_ge_u32 s30, s12
	s_cselect_b32 s9, s34, s9
	s_cselect_b32 s30, s31, s30
	s_add_i32 s31, s9, 1
	s_cmp_ge_u32 s30, s12
	s_cselect_b32 s9, s31, s9
	s_xor_b32 s9, s9, s13
	s_sub_i32 s9, s9, s13
	s_mul_i32 s12, s9, s12
	s_sub_i32 s12, s5, s12
	s_lshl_b32 s5, s9, 8
	s_lshl_b32 s12, s12, 6
	v_or_b32_e32 v28, s5, v2
	v_lshl_add_u32 v29, s9, 7, v6
	v_cndmask_b32_e64 v28, v28, v29, s[14:15]
	v_add_u32_e32 v29, s12, v5
	v_mad_i64_i32 v[30:31], s[14:15], s8, v29, 0
	v_ashrrev_i32_e32 v29, 31, v28
	v_lshl_add_u64 v[30:31], v[30:31], 2, s[10:11]
	v_lshlrev_b64 v[52:53], 2, v[28:29]
	v_lshl_add_u64 v[28:29], v[30:31], 0, v[52:53]
	v_add_u32_e32 v30, s12, v7
	v_add_u32_e32 v36, s12, v8
	v_add_u32_e32 v38, s12, v9
	v_add_u32_e32 v44, s12, v10
	v_add_u32_e32 v46, s12, v11
	v_add_u32_e32 v54, s12, v12
	v_add_u32_e32 v56, s12, v13
	v_mad_i64_i32 v[30:31], s[14:15], s8, v30, 0
	v_mad_i64_i32 v[36:37], s[14:15], s8, v36, 0
	v_mad_i64_i32 v[38:39], s[14:15], s8, v38, 0
	v_mad_i64_i32 v[44:45], s[14:15], s8, v44, 0
	v_mad_i64_i32 v[46:47], s[14:15], s8, v46, 0
	v_mad_i64_i32 v[54:55], s[14:15], s8, v54, 0
	v_mad_i64_i32 v[56:57], s[8:9], s8, v56, 0
	v_lshl_add_u64 v[30:31], v[30:31], 2, s[10:11]
	v_lshl_add_u64 v[36:37], v[36:37], 2, s[10:11]
	v_lshl_add_u64 v[38:39], v[38:39], 2, s[10:11]
	v_lshl_add_u64 v[44:45], v[44:45], 2, s[10:11]
	v_lshl_add_u64 v[46:47], v[46:47], 2, s[10:11]
	v_lshl_add_u64 v[54:55], v[54:55], 2, s[10:11]
	v_lshl_add_u64 v[56:57], v[56:57], 2, s[10:11]
	v_lshl_add_u64 v[32:33], v[30:31], 0, v[52:53]
	v_lshl_add_u64 v[36:37], v[36:37], 0, v[52:53]
	v_lshl_add_u64 v[40:41], v[38:39], 0, v[52:53]
	v_lshl_add_u64 v[44:45], v[44:45], 0, v[52:53]
	v_lshl_add_u64 v[48:49], v[46:47], 0, v[52:53]
	v_lshl_add_u64 v[54:55], v[54:55], 0, v[52:53]
	v_lshl_add_u64 v[56:57], v[56:57], 0, v[52:53]
	global_load_dwordx4 v[28:31], v[28:29], off nt
	s_nop 0
	global_load_dwordx4 v[32:35], v[32:33], off nt
	s_nop 0
	global_load_dwordx4 v[36:39], v[36:37], off nt
	s_nop 0
	global_load_dwordx4 v[40:43], v[40:41], off nt
	s_nop 0
	global_load_dwordx4 v[44:47], v[44:45], off nt
	s_nop 0
	global_load_dwordx4 v[48:51], v[48:49], off nt
	s_nop 0
	global_load_dwordx4 v[52:55], v[54:55], off nt
	s_nop 0
	global_load_dwordx4 v[56:59], v[56:57], off nt
	v_add_u32_e32 v60, s5, v3
	v_mad_i64_i32 v[60:61], s[8:9], s4, v60, 0
	s_ashr_i32 s13, s12, 31
	s_lshl_b64 s[8:9], s[12:13], 1
	s_add_u32 s6, s6, s8
	s_addc_u32 s7, s7, s9
	v_lshl_add_u64 v[62:63], s[6:7], 0, v[0:1]
	s_add_i32 s26, s26, s70
	s_cmpk_lt_i32 s26, 0x310
	s_waitcnt vmcnt(7)
	ds_write_b128 v14, v[28:31]
	s_waitcnt vmcnt(6)
	ds_write_b128 v15, v[32:35]
	s_waitcnt vmcnt(5)
	ds_write_b128 v16, v[36:39]
	s_waitcnt vmcnt(4)
	ds_write_b128 v17, v[40:43]
	s_waitcnt vmcnt(3)
	ds_write_b128 v18, v[44:47]
	s_waitcnt vmcnt(2)
	ds_write_b128 v19, v[48:51]
	s_waitcnt vmcnt(1)
	ds_write_b128 v20, v[52:55]
	s_waitcnt vmcnt(0)
	ds_write_b128 v21, v[56:59]
	s_waitcnt lgkmcnt(0)
	s_barrier
	ds_read_b32 v28, v4
	ds_read_b32 v29, v4 offset:1040
	ds_read_b32 v30, v4 offset:2080
	ds_read_b32 v31, v4 offset:3120
	ds_read_b32 v34, v4 offset:4160
	ds_read_b32 v35, v4 offset:5200
	ds_read_b32 v36, v4 offset:6240
	ds_read_b32 v37, v4 offset:7280
	s_waitcnt lgkmcnt(6)
	v_cvt_pk_bf16_f32 v28, v28, v29
	s_waitcnt lgkmcnt(4)
	v_cvt_pk_bf16_f32 v29, v30, v31
	s_waitcnt lgkmcnt(2)
	v_cvt_pk_bf16_f32 v30, v34, v35
	v_lshl_add_u64 v[32:33], v[60:61], 1, v[62:63]
	s_waitcnt lgkmcnt(0)
	v_cvt_pk_bf16_f32 v31, v36, v37
	ds_read_b32 v34, v23
	ds_read_b32 v35, v23 offset:1040
	ds_read_b32 v36, v23 offset:2080
	ds_read_b32 v37, v23 offset:3120
	ds_read_b32 v38, v23 offset:4160
	ds_read_b32 v39, v23 offset:5200
	ds_read_b32 v40, v23 offset:6240
	ds_read_b32 v41, v23 offset:7280
	global_store_dwordx4 v[32:33], v[28:31], off
	v_add_u32_e32 v32, s5, v22
	v_mad_i64_i32 v[32:33], s[6:7], s4, v32, 0
	s_waitcnt lgkmcnt(6)
	v_cvt_pk_bf16_f32 v28, v34, v35
	s_waitcnt lgkmcnt(4)
	v_cvt_pk_bf16_f32 v29, v36, v37
	s_waitcnt lgkmcnt(2)
	v_cvt_pk_bf16_f32 v30, v38, v39
	s_waitcnt lgkmcnt(0)
	v_cvt_pk_bf16_f32 v31, v40, v41
	ds_read_b32 v34, v25
	ds_read_b32 v35, v25 offset:1040
	ds_read_b32 v36, v25 offset:2080
	ds_read_b32 v37, v25 offset:3120
	ds_read_b32 v38, v25 offset:4160
	ds_read_b32 v39, v25 offset:5200
	ds_read_b32 v40, v25 offset:6240
	ds_read_b32 v41, v25 offset:7280
	v_lshl_add_u64 v[32:33], v[32:33], 1, v[62:63]
	global_store_dwordx4 v[32:33], v[28:31], off
	v_add_u32_e32 v32, s5, v24
	v_mad_i64_i32 v[32:33], s[6:7], s4, v32, 0
	s_waitcnt lgkmcnt(6)
	v_cvt_pk_bf16_f32 v28, v34, v35
	s_waitcnt lgkmcnt(4)
	v_cvt_pk_bf16_f32 v29, v36, v37
	s_waitcnt lgkmcnt(2)
	v_cvt_pk_bf16_f32 v30, v38, v39
	s_waitcnt lgkmcnt(0)
	v_cvt_pk_bf16_f32 v31, v40, v41
	ds_read_b32 v34, v27
	ds_read_b32 v35, v27 offset:1040
	ds_read_b32 v36, v27 offset:2080
	ds_read_b32 v37, v27 offset:3120
	ds_read_b32 v38, v27 offset:4160
	ds_read_b32 v39, v27 offset:5200
	ds_read_b32 v40, v27 offset:6240
	ds_read_b32 v41, v27 offset:7280
	v_lshl_add_u64 v[32:33], v[32:33], 1, v[62:63]
	global_store_dwordx4 v[32:33], v[28:31], off
	v_add_u32_e32 v32, s5, v26
	v_mad_i64_i32 v[32:33], s[4:5], s4, v32, 0
	s_waitcnt lgkmcnt(6)
	v_cvt_pk_bf16_f32 v28, v34, v35
	s_waitcnt lgkmcnt(4)
	v_cvt_pk_bf16_f32 v29, v36, v37
	s_waitcnt lgkmcnt(2)
	v_cvt_pk_bf16_f32 v30, v38, v39
	s_waitcnt lgkmcnt(0)
	v_cvt_pk_bf16_f32 v31, v40, v41
	v_lshl_add_u64 v[32:33], v[32:33], 1, v[62:63]
	global_store_dwordx4 v[32:33], v[28:31], off
	s_cbranch_scc0 .LBB0_955

; DI unsigned pack2(float lo, float hi) { const f32x2 v = (f32x2){lo, hi}; return __builtin_bit_cast(unsigned, __builtin_convertvector(v, bf16x2_t)); }
; DI void conv_jobs(const ConvJob j0, const ConvJob j1, const ConvJob j2, const ConvJob j3, char* shm) {
;     ...
;     for (int L = bx; L < c4; L += gridDim.x) {
;         const float* __restrict__ src = j0.src; bf16_t* __restrict__ dst = j0.dst; int ldsrc = j0.ldsrc, K = j0.K, mode = j0.mode, base = 0;
;         if (L >= c1) { src = j1.src; dst = j1.dst; ldsrc = j1.ldsrc; K = j1.K; mode = j1.mode; base = c1; }
;         if (L >= c2) { src = j2.src; dst = j2.dst; ldsrc = j2.ldsrc; K = j2.K; mode = j2.mode; base = c2; }
;         if (L >= c3) { src = j3.src; dst = j3.dst; ldsrc = j3.ldsrc; K = j3.K; mode = j3.mode; base = c3; }
;         const int nk = K / 64, Ll = L - base, tk = Ll % nk, ts = Ll / nk, n0 = ts * 256;
;         __syncthreads();
;         f32x4 v[8];
; #pragma unroll
;         for (int i = 0; i < 8; ++i) { const int e = tid + i * NTHR, kk = e >> 6, n4 = (e & 63) * 4;
;             const int scol = mode == 1 ? ((n4 >> 7) ? 2816 + ts * 128 + (n4 & 127) : ts * 128 + n4) : n0 + n4;
;             v[i] = *(const f32x4*)(src + (size_t)(tk * 64 + kk) * ldsrc + scol); }
; #pragma unroll
;         for (int i = 0; i < 8; ++i) { const int e = tid + i * NTHR, kk = e >> 6, n4 = (e & 63) * 4; *(f32x4*)(tile + kk * 260 + (n4 ^ (((kk >> 3) & 7) << 3))) = v[i]; }
;         __syncthreads();
; #pragma unroll
;         for (int i = 0; i < 4; ++i) { const int n = (tid >> 3) + 64 * i, m = tid & 7, kc = m * 8; const float* tp = tile + kc * 260 + (n ^ (m << 3)); u32x4 w;
;             w.x = pack2(tp[0], tp[260]); w.y = pack2(tp[2 * 260], tp[3 * 260]); w.z = pack2(tp[4 * 260], tp[5 * 260]); w.w = pack2(tp[6 * 260], tp[7 * 260]);
;             *(u32x4*)(dst + (size_t)(n0 + n) * K + tk * 64 + kc) = w; }
.LBB0_1879:
	v_cvt_f32_ubyte0_e32 v28, s12
	v_rcp_iflag_f32_e32 v28, v28
	s_sub_i32 s9, 0, s12
	s_add_i32 s5, s26, s5
	s_abs_i32 s30, s5
	v_mul_f32_e32 v28, 0x4f7ffffe, v28
	v_cvt_u32_f32_e32 v28, v28
	s_ashr_i32 s13, s5, 31
	s_barrier
	v_readfirstlane_b32 s31, v28
	s_mul_i32 s9, s9, s31
	s_mul_hi_u32 s9, s31, s9
	s_add_i32 s31, s31, s9
	s_mul_hi_u32 s9, s30, s31
	s_mul_i32 s31, s9, s12
	s_sub_i32 s30, s30, s31
	s_add_i32 s34, s9, 1
	s_sub_i32 s31, s30, s12
	s_cmp_ge_u32 s30, s12
	s_cselect_b32 s9, s34, s9
	s_cselect_b32 s30, s31, s30
	s_add_i32 s31, s9, 1
	s_cmp_ge_u32 s30, s12
	s_cselect_b32 s9, s31, s9
	s_xor_b32 s9, s9, s13
	s_sub_i32 s9, s9, s13
	s_mul_i32 s12, s9, s12
	s_sub_i32 s12, s5, s12
	s_lshl_b32 s5, s9, 8
	s_lshl_b32 s12, s12, 6
	v_or_b32_e32 v28, s5, v2
	v_lshl_add_u32 v29, s9, 7, v6
	v_cndmask_b32_e64 v28, v28, v29, s[14:15]
	v_add_u32_e32 v29, s12, v5
	v_mad_i64_i32 v[30:31], s[14:15], s8, v29, 0
	v_ashrrev_i32_e32 v29, 31, v28
	v_lshl_add_u64 v[30:31], v[30:31], 2, s[10:11]
	v_lshlrev_b64 v[52:53], 2, v[28:29]
	v_lshl_add_u64 v[28:29], v[30:31], 0, v[52:53]
	v_add_u32_e32 v30, s12, v7
	v_add_u32_e32 v36, s12, v8
	v_add_u32_e32 v38, s12, v9
	v_add_u32_e32 v44, s12, v10
	v_add_u32_e32 v46, s12, v11
	v_add_u32_e32 v54, s12, v12
	v_add_u32_e32 v56, s12, v13
	v_mad_i64_i32 v[30:31], s[14:15], s8, v30, 0
	v_mad_i64_i32 v[36:37], s[14:15], s8, v36, 0
	v_mad_i64_i32 v[38:39], s[14:15], s8, v38, 0
	v_mad_i64_i32 v[44:45], s[14:15], s8, v44, 0
	v_mad_i64_i32 v[46:47], s[14:15], s8, v46, 0
	v_mad_i64_i32 v[54:55], s[14:15], s8, v54, 0
	v_mad_i64_i32 v[56:57], s[8:9], s8, v56, 0
	v_lshl_add_u64 v[30:31], v[30:31], 2, s[10:11]
	v_lshl_add_u64 v[36:37], v[36:37], 2, s[10:11]
	v_lshl_add_u64 v[38:39], v[38:39], 2, s[10:11]
	v_lshl_add_u64 v[44:45], v[44:45], 2, s[10:11]
	v_lshl_add_u64 v[46:47], v[46:47], 2, s[10:11]
	v_lshl_add_u64 v[54:55], v[54:55], 2, s[10:11]
	v_lshl_add_u64 v[56:57], v[56:57], 2, s[10:11]
	v_lshl_add_u64 v[32:33], v[30:31], 0, v[52:53]
	v_lshl_add_u64 v[36:37], v[36:37], 0, v[52:53]
	v_lshl_add_u64 v[40:41], v[38:39], 0, v[52:53]
	v_lshl_add_u64 v[44:45], v[44:45], 0, v[52:53]
	v_lshl_add_u64 v[48:49], v[46:47], 0, v[52:53]
	v_lshl_add_u64 v[54:55], v[54:55], 0, v[52:53]
	v_lshl_add_u64 v[56:57], v[56:57], 0, v[52:53]
	global_load_dwordx4 v[28:31], v[28:29], off nt
	s_nop 0
	global_load_dwordx4 v[32:35], v[32:33], off nt
	s_nop 0
	global_load_dwordx4 v[36:39], v[36:37], off nt
	s_nop 0
	global_load_dwordx4 v[40:43], v[40:41], off nt
	s_nop 0
	global_load_dwordx4 v[44:47], v[44:45], off nt
	s_nop 0
	global_load_dwordx4 v[48:51], v[48:49], off nt
	s_nop 0
	global_load_dwordx4 v[52:55], v[54:55], off nt
	s_nop 0
	global_load_dwordx4 v[56:59], v[56:57], off nt
	v_add_u32_e32 v60, s5, v3
	v_mad_i64_i32 v[60:61], s[8:9], s4, v60, 0
	s_ashr_i32 s13, s12, 31
	s_lshl_b64 s[8:9], s[12:13], 1
	s_add_u32 s6, s6, s8
	s_addc_u32 s7, s7, s9
	v_lshl_add_u64 v[62:63], s[6:7], 0, v[0:1]
	s_add_i32 s26, s26, s70
	s_cmpk_lt_i32 s26, 0x390
	s_waitcnt vmcnt(7)
	ds_write_b128 v14, v[28:31]
	s_waitcnt vmcnt(6)
	ds_write_b128 v15, v[32:35]
	s_waitcnt vmcnt(5)
	ds_write_b128 v16, v[36:39]
	s_waitcnt vmcnt(4)
	ds_write_b128 v17, v[40:43]
	s_waitcnt vmcnt(3)
	ds_write_b128 v18, v[44:47]
	s_waitcnt vmcnt(2)
	ds_write_b128 v19, v[48:51]
	s_waitcnt vmcnt(1)
	ds_write_b128 v20, v[52:55]
	s_waitcnt vmcnt(0)
	ds_write_b128 v21, v[56:59]
	s_waitcnt lgkmcnt(0)
	s_barrier
	ds_read_b32 v28, v4
	ds_read_b32 v29, v4 offset:1040
	ds_read_b32 v30, v4 offset:2080
	ds_read_b32 v31, v4 offset:3120
	ds_read_b32 v34, v4 offset:4160
	ds_read_b32 v35, v4 offset:5200
	ds_read_b32 v36, v4 offset:6240
	ds_read_b32 v37, v4 offset:7280
	s_waitcnt lgkmcnt(6)
	v_cvt_pk_bf16_f32 v28, v28, v29
	s_waitcnt lgkmcnt(4)
	v_cvt_pk_bf16_f32 v29, v30, v31
	s_waitcnt lgkmcnt(2)
	v_cvt_pk_bf16_f32 v30, v34, v35
	v_lshl_add_u64 v[32:33], v[60:61], 1, v[62:63]
	s_waitcnt lgkmcnt(0)
	v_cvt_pk_bf16_f32 v31, v36, v37
	ds_read_b32 v34, v23
	ds_read_b32 v35, v23 offset:1040
	ds_read_b32 v36, v23 offset:2080
	ds_read_b32 v37, v23 offset:3120
	ds_read_b32 v38, v23 offset:4160
	ds_read_b32 v39, v23 offset:5200
	ds_read_b32 v40, v23 offset:6240
	ds_read_b32 v41, v23 offset:7280
	global_store_dwordx4 v[32:33], v[28:31], off
	v_add_u32_e32 v32, s5, v22
	v_mad_i64_i32 v[32:33], s[6:7], s4, v32, 0
	s_waitcnt lgkmcnt(6)
	v_cvt_pk_bf16_f32 v28, v34, v35
	s_waitcnt lgkmcnt(4)
	v_cvt_pk_bf16_f32 v29, v36, v37
	s_waitcnt lgkmcnt(2)
	v_cvt_pk_bf16_f32 v30, v38, v39
	s_waitcnt lgkmcnt(0)
	v_cvt_pk_bf16_f32 v31, v40, v41
	ds_read_b32 v34, v25
	ds_read_b32 v35, v25 offset:1040
	ds_read_b32 v36, v25 offset:2080
	ds_read_b32 v37, v25 offset:3120
	ds_read_b32 v38, v25 offset:4160
	ds_read_b32 v39, v25 offset:5200
	ds_read_b32 v40, v25 offset:6240
	ds_read_b32 v41, v25 offset:7280
	v_lshl_add_u64 v[32:33], v[32:33], 1, v[62:63]
	global_store_dwordx4 v[32:33], v[28:31], off
	v_add_u32_e32 v32, s5, v24
	v_mad_i64_i32 v[32:33], s[6:7], s4, v32, 0
	s_waitcnt lgkmcnt(6)
	v_cvt_pk_bf16_f32 v28, v34, v35
	s_waitcnt lgkmcnt(4)
	v_cvt_pk_bf16_f32 v29, v36, v37
	s_waitcnt lgkmcnt(2)
	v_cvt_pk_bf16_f32 v30, v38, v39
	s_waitcnt lgkmcnt(0)
	v_cvt_pk_bf16_f32 v31, v40, v41
	ds_read_b32 v34, v27
	ds_read_b32 v35, v27 offset:1040
	ds_read_b32 v36, v27 offset:2080
	ds_read_b32 v37, v27 offset:3120
	ds_read_b32 v38, v27 offset:4160
	ds_read_b32 v39, v27 offset:5200
	ds_read_b32 v40, v27 offset:6240
	ds_read_b32 v41, v27 offset:7280
	v_lshl_add_u64 v[32:33], v[32:33], 1, v[62:63]
	global_store_dwordx4 v[32:33], v[28:31], off
	v_add_u32_e32 v32, s5, v26
	v_mad_i64_i32 v[32:33], s[4:5], s4, v32, 0
	s_waitcnt lgkmcnt(6)
	v_cvt_pk_bf16_f32 v28, v34, v35
	s_waitcnt lgkmcnt(4)
	v_cvt_pk_bf16_f32 v29, v36, v37
	s_waitcnt lgkmcnt(2)
	v_cvt_pk_bf16_f32 v30, v38, v39
	s_waitcnt lgkmcnt(0)
	v_cvt_pk_bf16_f32 v31, v40, v41
	v_lshl_add_u64 v[32:33], v[32:33], 1, v[62:63]
	global_store_dwordx4 v[32:33], v[28:31], off
	s_cbranch_scc0 .LBB0_1886

; DI unsigned pack2(float lo, float hi) { const f32x2 v = (f32x2){lo, hi}; return __builtin_bit_cast(unsigned, __builtin_convertvector(v, bf16x2_t)); }
; DI void conv_jobs(const ConvJob j0, const ConvJob j1, const ConvJob j2, const ConvJob j3, char* shm) {
;     ...
;     for (int L = bx; L < c4; L += gridDim.x) {
;         const float* __restrict__ src = j0.src; bf16_t* __restrict__ dst = j0.dst; int ldsrc = j0.ldsrc, K = j0.K, mode = j0.mode, base = 0;
;         if (L >= c1) { src = j1.src; dst = j1.dst; ldsrc = j1.ldsrc; K = j1.K; mode = j1.mode; base = c1; }
;         if (L >= c2) { src = j2.src; dst = j2.dst; ldsrc = j2.ldsrc; K = j2.K; mode = j2.mode; base = c2; }
;         if (L >= c3) { src = j3.src; dst = j3.dst; ldsrc = j3.ldsrc; K = j3.K; mode = j3.mode; base = c3; }
;         const int nk = K / 64, Ll = L - base, tk = Ll % nk, ts = Ll / nk, n0 = ts * 256;
;         __syncthreads();
;         f32x4 v[8];
; #pragma unroll
;         for (int i = 0; i < 8; ++i) { const int e = tid + i * NTHR, kk = e >> 6, n4 = (e & 63) * 4;
;             const int scol = mode == 1 ? ((n4 >> 7) ? 2816 + ts * 128 + (n4 & 127) : ts * 128 + n4) : n0 + n4;
;             v[i] = *(const f32x4*)(src + (size_t)(tk * 64 + kk) * ldsrc + scol); }
; #pragma unroll
;         for (int i = 0; i < 8; ++i) { const int e = tid + i * NTHR, kk = e >> 6, n4 = (e & 63) * 4; *(f32x4*)(tile + kk * 260 + (n4 ^ (((kk >> 3) & 7) << 3))) = v[i]; }
;         __syncthreads();
; #pragma unroll
;         for (int i = 0; i < 4; ++i) { const int n = (tid >> 3) + 64 * i, m = tid & 7, kc = m * 8; const float* tp = tile + kc * 260 + (n ^ (m << 3)); u32x4 w;
;             w.x = pack2(tp[0], tp[260]); w.y = pack2(tp[2 * 260], tp[3 * 260]); w.z = pack2(tp[4 * 260], tp[5 * 260]); w.w = pack2(tp[6 * 260], tp[7 * 260]);
;             *(u32x4*)(dst + (size_t)(n0 + n) * K + tk * 64 + kc) = w; }
.LBB0_2990:
	v_cvt_f32_ubyte0_e32 v28, s12
	v_rcp_iflag_f32_e32 v28, v28
	s_sub_i32 s9, 0, s12
	s_add_i32 s5, s26, s5
	s_abs_i32 s30, s5
	v_mul_f32_e32 v28, 0x4f7ffffe, v28
	v_cvt_u32_f32_e32 v28, v28
	s_ashr_i32 s13, s5, 31
	s_barrier
	v_readfirstlane_b32 s31, v28
	s_mul_i32 s9, s9, s31
	s_mul_hi_u32 s9, s31, s9
	s_add_i32 s31, s31, s9
	s_mul_hi_u32 s9, s30, s31
	s_mul_i32 s31, s9, s12
	s_sub_i32 s30, s30, s31
	s_add_i32 s34, s9, 1
	s_sub_i32 s31, s30, s12
	s_cmp_ge_u32 s30, s12
	s_cselect_b32 s9, s34, s9
	s_cselect_b32 s30, s31, s30
	s_add_i32 s31, s9, 1
	s_cmp_ge_u32 s30, s12
	s_cselect_b32 s9, s31, s9
	s_xor_b32 s9, s9, s13
	s_sub_i32 s9, s9, s13
	s_mul_i32 s12, s9, s12
	s_sub_i32 s12, s5, s12
	s_lshl_b32 s5, s9, 8
	s_lshl_b32 s12, s12, 6
	v_or_b32_e32 v28, s5, v2
	v_lshl_add_u32 v29, s9, 7, v6
	v_cndmask_b32_e64 v28, v28, v29, s[14:15]
	v_add_u32_e32 v29, s12, v5
	v_mad_i64_i32 v[30:31], s[14:15], s8, v29, 0
	v_ashrrev_i32_e32 v29, 31, v28
	v_lshl_add_u64 v[30:31], v[30:31], 2, s[10:11]
	v_lshlrev_b64 v[52:53], 2, v[28:29]
	v_lshl_add_u64 v[28:29], v[30:31], 0, v[52:53]
	v_add_u32_e32 v30, s12, v7
	v_add_u32_e32 v36, s12, v8
	v_add_u32_e32 v38, s12, v9
	v_add_u32_e32 v44, s12, v10
	v_add_u32_e32 v46, s12, v11
	v_add_u32_e32 v54, s12, v12
	v_add_u32_e32 v56, s12, v13
	v_mad_i64_i32 v[30:31], s[14:15], s8, v30, 0
	v_mad_i64_i32 v[36:37], s[14:15], s8, v36, 0
	v_mad_i64_i32 v[38:39], s[14:15], s8, v38, 0
	v_mad_i64_i32 v[44:45], s[14:15], s8, v44, 0
	v_mad_i64_i32 v[46:47], s[14:15], s8, v46, 0
	v_mad_i64_i32 v[54:55], s[14:15], s8, v54, 0
	v_mad_i64_i32 v[56:57], s[8:9], s8, v56, 0
	v_lshl_add_u64 v[30:31], v[30:31], 2, s[10:11]
	v_lshl_add_u64 v[36:37], v[36:37], 2, s[10:11]
	v_lshl_add_u64 v[38:39], v[38:39], 2, s[10:11]
	v_lshl_add_u64 v[44:45], v[44:45], 2, s[10:11]
	v_lshl_add_u64 v[46:47], v[46:47], 2, s[10:11]
	v_lshl_add_u64 v[54:55], v[54:55], 2, s[10:11]
	v_lshl_add_u64 v[56:57], v[56:57], 2, s[10:11]
	v_lshl_add_u64 v[32:33], v[30:31], 0, v[52:53]
	v_lshl_add_u64 v[36:37], v[36:37], 0, v[52:53]
	v_lshl_add_u64 v[40:41], v[38:39], 0, v[52:53]
	v_lshl_add_u64 v[44:45], v[44:45], 0, v[52:53]
	v_lshl_add_u64 v[48:49], v[46:47], 0, v[52:53]
	v_lshl_add_u64 v[54:55], v[54:55], 0, v[52:53]
	v_lshl_add_u64 v[56:57], v[56:57], 0, v[52:53]
	global_load_dwordx4 v[28:31], v[28:29], off nt
	s_nop 0
	global_load_dwordx4 v[32:35], v[32:33], off nt
	s_nop 0
	global_load_dwordx4 v[36:39], v[36:37], off nt
	s_nop 0
	global_load_dwordx4 v[40:43], v[40:41], off nt
	s_nop 0
	global_load_dwordx4 v[44:47], v[44:45], off nt
	s_nop 0
	global_load_dwordx4 v[48:51], v[48:49], off nt
	s_nop 0
	global_load_dwordx4 v[52:55], v[54:55], off nt
	s_nop 0
	global_load_dwordx4 v[56:59], v[56:57], off nt
	v_add_u32_e32 v60, s5, v3
	v_mad_i64_i32 v[60:61], s[8:9], s4, v60, 0
	s_ashr_i32 s13, s12, 31
	s_lshl_b64 s[8:9], s[12:13], 1
	s_add_u32 s6, s6, s8
	s_addc_u32 s7, s7, s9
	v_lshl_add_u64 v[62:63], s[6:7], 0, v[0:1]
	s_add_i32 s26, s26, s70
	s_cmpk_lt_i32 s26, 0x2b0
	s_waitcnt vmcnt(7)
	ds_write_b128 v14, v[28:31]
	s_waitcnt vmcnt(6)
	ds_write_b128 v15, v[32:35]
	s_waitcnt vmcnt(5)
	ds_write_b128 v16, v[36:39]
	s_waitcnt vmcnt(4)
	ds_write_b128 v17, v[40:43]
	s_waitcnt vmcnt(3)
	ds_write_b128 v18, v[44:47]
	s_waitcnt vmcnt(2)
	ds_write_b128 v19, v[48:51]
	s_waitcnt vmcnt(1)
	ds_write_b128 v20, v[52:55]
	s_waitcnt vmcnt(0)
	ds_write_b128 v21, v[56:59]
	s_waitcnt lgkmcnt(0)
	s_barrier
	ds_read_b32 v28, v4
	ds_read_b32 v29, v4 offset:1040
	ds_read_b32 v30, v4 offset:2080
	ds_read_b32 v31, v4 offset:3120
	ds_read_b32 v34, v4 offset:4160
	ds_read_b32 v35, v4 offset:5200
	ds_read_b32 v36, v4 offset:6240
	ds_read_b32 v37, v4 offset:7280
	s_waitcnt lgkmcnt(6)
	v_cvt_pk_bf16_f32 v28, v28, v29
	s_waitcnt lgkmcnt(4)
	v_cvt_pk_bf16_f32 v29, v30, v31
	s_waitcnt lgkmcnt(2)
	v_cvt_pk_bf16_f32 v30, v34, v35
	v_lshl_add_u64 v[32:33], v[60:61], 1, v[62:63]
	s_waitcnt lgkmcnt(0)
	v_cvt_pk_bf16_f32 v31, v36, v37
	ds_read_b32 v34, v23
	ds_read_b32 v35, v23 offset:1040
	ds_read_b32 v36, v23 offset:2080
	ds_read_b32 v37, v23 offset:3120
	ds_read_b32 v38, v23 offset:4160
	ds_read_b32 v39, v23 offset:5200
	ds_read_b32 v40, v23 offset:6240
	ds_read_b32 v41, v23 offset:7280
	global_store_dwordx4 v[32:33], v[28:31], off
	v_add_u32_e32 v32, s5, v22
	v_mad_i64_i32 v[32:33], s[6:7], s4, v32, 0
	s_waitcnt lgkmcnt(6)
	v_cvt_pk_bf16_f32 v28, v34, v35
	s_waitcnt lgkmcnt(4)
	v_cvt_pk_bf16_f32 v29, v36, v37
	s_waitcnt lgkmcnt(2)
	v_cvt_pk_bf16_f32 v30, v38, v39
	s_waitcnt lgkmcnt(0)
	v_cvt_pk_bf16_f32 v31, v40, v41
	ds_read_b32 v34, v25
	ds_read_b32 v35, v25 offset:1040
	ds_read_b32 v36, v25 offset:2080
	ds_read_b32 v37, v25 offset:3120
	ds_read_b32 v38, v25 offset:4160
	ds_read_b32 v39, v25 offset:5200
	ds_read_b32 v40, v25 offset:6240
	ds_read_b32 v41, v25 offset:7280
	v_lshl_add_u64 v[32:33], v[32:33], 1, v[62:63]
	global_store_dwordx4 v[32:33], v[28:31], off
	v_add_u32_e32 v32, s5, v24
	v_mad_i64_i32 v[32:33], s[6:7], s4, v32, 0
	s_waitcnt lgkmcnt(6)
	v_cvt_pk_bf16_f32 v28, v34, v35
	s_waitcnt lgkmcnt(4)
	v_cvt_pk_bf16_f32 v29, v36, v37
	s_waitcnt lgkmcnt(2)
	v_cvt_pk_bf16_f32 v30, v38, v39
	s_waitcnt lgkmcnt(0)
	v_cvt_pk_bf16_f32 v31, v40, v41
	ds_read_b32 v34, v27
	ds_read_b32 v35, v27 offset:1040
	ds_read_b32 v36, v27 offset:2080
	ds_read_b32 v37, v27 offset:3120
	ds_read_b32 v38, v27 offset:4160
	ds_read_b32 v39, v27 offset:5200
	ds_read_b32 v40, v27 offset:6240
	ds_read_b32 v41, v27 offset:7280
	v_lshl_add_u64 v[32:33], v[32:33], 1, v[62:63]
	global_store_dwordx4 v[32:33], v[28:31], off
	v_add_u32_e32 v32, s5, v26
	v_mad_i64_i32 v[32:33], s[4:5], s4, v32, 0
	s_waitcnt lgkmcnt(6)
	v_cvt_pk_bf16_f32 v28, v34, v35
	s_waitcnt lgkmcnt(4)
	v_cvt_pk_bf16_f32 v29, v36, v37
	s_waitcnt lgkmcnt(2)
	v_cvt_pk_bf16_f32 v30, v38, v39
	s_waitcnt lgkmcnt(0)
	v_cvt_pk_bf16_f32 v31, v40, v41
	v_lshl_add_u64 v[32:33], v[32:33], 1, v[62:63]
	global_store_dwordx4 v[32:33], v[28:31], off
	s_cbranch_scc0 .LBB0_2997
